# P8 panel exchange: dropped the L2/L1 invalidate after the counter wait (the partial sums are read with sc1 loads; no other cross-workgroup data is read afterwards)
# baseline (speedup 1.0000x reference)
.LBB0_1664:
	s_waitcnt vmcnt(0)
	v_mov_b32_e32 v130, s93
	ds_write_b32 v130, v228
